# grid barrier: XCD leader releases the per-XCD generation before its own acquire invalidate (23 sites)
# baseline (speedup 1.0000x reference)
; __device__ __forceinline__ unsigned xb_add(unsigned* p, unsigned v) { return __hip_atomic_fetch_add(p, v, __ATOMIC_RELAXED, __HIP_MEMORY_SCOPE_AGENT); }
; __device__ __forceinline__ void xcd_barrier(const XcdBarrier& b) {
;     ...
;             __builtin_amdgcn_fence(__ATOMIC_ACQUIRE, "");
;             xb_add(&bar[XB_XGEN(b.x)], 1u);
;             asm volatile("s_waitcnt vmcnt(0)" ::: "memory");
.LBB0_243:
	s_or_b64 exec, exec, s[8:9]
	s_mov_b64 s[8:9], exec
	v_mbcnt_lo_u32_b32 v0, s8, 0
	v_mbcnt_hi_u32_b32 v0, s9, v0
	v_cmp_eq_u32_e32 vcc, 0, v0
	s_waitcnt vmcnt(0)
	s_and_saveexec_b64 s[10:11], vcc
	s_cbranch_execz .LBB0_245
	s_bcnt1_i32_b64 s3, s[8:9]
	v_mov_b32_e32 v0, 0x2000
	v_mov_b32_e32 v1, s3
	global_atomic_add v0, v1, s[4:5] offset:1024
.LBB0_245:
	s_or_b64 exec, exec, s[10:11]
	buffer_inv sc0 sc1
	s_waitcnt vmcnt(0)

; __device__ __forceinline__ unsigned xb_add(unsigned* p, unsigned v) { return __hip_atomic_fetch_add(p, v, __ATOMIC_RELAXED, __HIP_MEMORY_SCOPE_AGENT); }
; __device__ __forceinline__ void xcd_barrier(const XcdBarrier& b) {
;     ...
;             __builtin_amdgcn_fence(__ATOMIC_ACQUIRE, "");
;             xb_add(&bar[XB_XGEN(b.x)], 1u);
;             asm volatile("s_waitcnt vmcnt(0)" ::: "memory");
.LBB0_312:
	s_or_b64 exec, exec, s[8:9]
	s_mov_b64 s[8:9], exec
	v_mbcnt_lo_u32_b32 v0, s8, 0
	v_mbcnt_hi_u32_b32 v0, s9, v0
	v_cmp_eq_u32_e32 vcc, 0, v0
	s_waitcnt vmcnt(0)
	s_and_saveexec_b64 s[10:11], vcc
	s_cbranch_execz .LBB0_314
	s_bcnt1_i32_b64 s8, s[8:9]
	v_mov_b32_e32 v0, 0x2000
	v_mov_b32_e32 v1, s8
	global_atomic_add v0, v1, s[4:5] offset:1024

; __device__ __forceinline__ unsigned xb_add(unsigned* p, unsigned v) { return __hip_atomic_fetch_add(p, v, __ATOMIC_RELAXED, __HIP_MEMORY_SCOPE_AGENT); }
; __device__ __forceinline__ void xcd_barrier(const XcdBarrier& b) {
;     ...
;             __builtin_amdgcn_fence(__ATOMIC_ACQUIRE, "");
;             xb_add(&bar[XB_XGEN(b.x)], 1u);
;             asm volatile("s_waitcnt vmcnt(0)" ::: "memory");
.LBB0_414:
	s_or_b64 exec, exec, s[6:7]
	s_mov_b64 s[6:7], exec
	v_mbcnt_lo_u32_b32 v0, s6, 0
	v_mbcnt_hi_u32_b32 v0, s7, v0
	v_cmp_eq_u32_e32 vcc, 0, v0
	s_waitcnt vmcnt(0)
	s_and_saveexec_b64 s[8:9], vcc
	s_cbranch_execz .LBB0_416
	s_bcnt1_i32_b64 s6, s[6:7]
	v_mov_b32_e32 v0, 0x2000
	v_mov_b32_e32 v1, s6
	global_atomic_add v0, v1, s[4:5] offset:1024
.LBB0_416:
	s_or_b64 exec, exec, s[8:9]
	buffer_inv sc0 sc1
	s_waitcnt vmcnt(0)

; __device__ __forceinline__ unsigned xb_add(unsigned* p, unsigned v) { return __hip_atomic_fetch_add(p, v, __ATOMIC_RELAXED, __HIP_MEMORY_SCOPE_AGENT); }
; __device__ __forceinline__ void xcd_barrier(const XcdBarrier& b) {
;     ...
;             __builtin_amdgcn_fence(__ATOMIC_ACQUIRE, "");
;             xb_add(&bar[XB_XGEN(b.x)], 1u);
;             asm volatile("s_waitcnt vmcnt(0)" ::: "memory");
.LBB0_689:
	s_or_b64 exec, exec, s[8:9]
	s_mov_b64 s[8:9], exec
	v_mbcnt_lo_u32_b32 v0, s8, 0
	v_mbcnt_hi_u32_b32 v0, s9, v0
	v_cmp_eq_u32_e32 vcc, 0, v0
	s_waitcnt vmcnt(0)
	s_and_saveexec_b64 s[10:11], vcc
	s_cbranch_execz .LBB0_691
	s_bcnt1_i32_b64 s8, s[8:9]
	v_mov_b32_e32 v0, 0x2000
	v_mov_b32_e32 v1, s8
	global_atomic_add v0, v1, s[6:7] offset:1024

; __device__ __forceinline__ unsigned xb_add(unsigned* p, unsigned v) { return __hip_atomic_fetch_add(p, v, __ATOMIC_RELAXED, __HIP_MEMORY_SCOPE_AGENT); }
; __device__ __forceinline__ void xcd_barrier(const XcdBarrier& b) {
;     ...
;             __builtin_amdgcn_fence(__ATOMIC_ACQUIRE, "");
;             xb_add(&bar[XB_XGEN(b.x)], 1u);
;             asm volatile("s_waitcnt vmcnt(0)" ::: "memory");
.LBB0_822:
	s_or_b64 exec, exec, s[12:13]
	s_mov_b64 s[12:13], exec
	v_mbcnt_lo_u32_b32 v0, s12, 0
	v_mbcnt_hi_u32_b32 v0, s13, v0
	v_cmp_eq_u32_e32 vcc, 0, v0
	s_waitcnt vmcnt(0)
	s_and_saveexec_b64 s[22:23], vcc
	s_cbranch_execz .LBB0_824
	s_bcnt1_i32_b64 s12, s[12:13]
	v_mov_b32_e32 v0, 0x2000
	v_mov_b32_e32 v1, s12
	global_atomic_add v0, v1, s[10:11] offset:1024
.LBB0_824:
	s_or_b64 exec, exec, s[22:23]
	buffer_inv sc0 sc1
	s_waitcnt vmcnt(0)

; __device__ __forceinline__ unsigned xb_add(unsigned* p, unsigned v) { return __hip_atomic_fetch_add(p, v, __ATOMIC_RELAXED, __HIP_MEMORY_SCOPE_AGENT); }
; __device__ __forceinline__ void xcd_barrier(const XcdBarrier& b) {
;     ...
;             __builtin_amdgcn_fence(__ATOMIC_ACQUIRE, "");
;             xb_add(&bar[XB_XGEN(b.x)], 1u);
;             asm volatile("s_waitcnt vmcnt(0)" ::: "memory");
.LBB0_1031:
	s_or_b64 exec, exec, s[10:11]
	s_mov_b64 s[10:11], exec
	v_mbcnt_lo_u32_b32 v0, s10, 0
	v_mbcnt_hi_u32_b32 v0, s11, v0
	v_cmp_eq_u32_e32 vcc, 0, v0
	s_waitcnt vmcnt(0)
	s_and_saveexec_b64 s[12:13], vcc
	s_cbranch_execz .LBB0_1033
	s_bcnt1_i32_b64 s10, s[10:11]
	v_mov_b32_e32 v0, 0x2000
	v_mov_b32_e32 v1, s10
	global_atomic_add v0, v1, s[6:7] offset:1024
.LBB0_1033:
	s_or_b64 exec, exec, s[12:13]
	buffer_inv sc0 sc1
	s_waitcnt vmcnt(0)

; __device__ __forceinline__ unsigned xb_add(unsigned* p, unsigned v) { return __hip_atomic_fetch_add(p, v, __ATOMIC_RELAXED, __HIP_MEMORY_SCOPE_AGENT); }
; __device__ __forceinline__ void xcd_barrier(const XcdBarrier& b) {
;     ...
;             __builtin_amdgcn_fence(__ATOMIC_ACQUIRE, "");
;             xb_add(&bar[XB_XGEN(b.x)], 1u);
;             asm volatile("s_waitcnt vmcnt(0)" ::: "memory");
.LBB0_1100:
	s_or_b64 exec, exec, s[12:13]
	s_mov_b64 s[12:13], exec
	v_mbcnt_lo_u32_b32 v0, s12, 0
	v_mbcnt_hi_u32_b32 v0, s13, v0
	v_cmp_eq_u32_e32 vcc, 0, v0
	s_waitcnt vmcnt(0)
	s_and_saveexec_b64 s[22:23], vcc
	s_cbranch_execz .LBB0_1102
	s_bcnt1_i32_b64 s12, s[12:13]
	v_mov_b32_e32 v0, 0x2000
	v_mov_b32_e32 v1, s12
	global_atomic_add v0, v1, s[6:7] offset:1024

; __device__ __forceinline__ unsigned xb_add(unsigned* p, unsigned v) { return __hip_atomic_fetch_add(p, v, __ATOMIC_RELAXED, __HIP_MEMORY_SCOPE_AGENT); }
; __device__ __forceinline__ void xcd_barrier(const XcdBarrier& b) {
;     ...
;             __builtin_amdgcn_fence(__ATOMIC_ACQUIRE, "");
;             xb_add(&bar[XB_XGEN(b.x)], 1u);
;             asm volatile("s_waitcnt vmcnt(0)" ::: "memory");
.LBB0_1179:
	s_or_b64 exec, exec, s[8:9]
	s_mov_b64 s[8:9], exec
	v_mbcnt_lo_u32_b32 v0, s8, 0
	v_mbcnt_hi_u32_b32 v0, s9, v0
	v_cmp_eq_u32_e32 vcc, 0, v0
	s_waitcnt vmcnt(0)
	s_and_saveexec_b64 s[12:13], vcc
	s_cbranch_execz .LBB0_1181
	s_bcnt1_i32_b64 s8, s[8:9]
	v_mov_b32_e32 v0, 0x2000
	v_mov_b32_e32 v1, s8
	global_atomic_add v0, v1, s[6:7] offset:1024

; __device__ __forceinline__ unsigned xb_add(unsigned* p, unsigned v) { return __hip_atomic_fetch_add(p, v, __ATOMIC_RELAXED, __HIP_MEMORY_SCOPE_AGENT); }
; __device__ __forceinline__ void xcd_barrier(const XcdBarrier& b) {
;     ...
;             __builtin_amdgcn_fence(__ATOMIC_ACQUIRE, "");
;             xb_add(&bar[XB_XGEN(b.x)], 1u);
;             asm volatile("s_waitcnt vmcnt(0)" ::: "memory");
.LBB0_1850:
	s_or_b64 exec, exec, s[12:13]
	s_mov_b64 s[12:13], exec
	v_mbcnt_lo_u32_b32 v0, s12, 0
	v_mbcnt_hi_u32_b32 v0, s13, v0
	v_cmp_eq_u32_e32 vcc, 0, v0
	s_waitcnt vmcnt(0)
	s_and_saveexec_b64 s[20:21], vcc
	s_cbranch_execz .LBB0_1852
	s_bcnt1_i32_b64 s12, s[12:13]
	v_mov_b32_e32 v0, 0x2000
	v_mov_b32_e32 v1, s12
	global_atomic_add v0, v1, s[6:7] offset:1024
.LBB0_1852:
	s_or_b64 exec, exec, s[20:21]
	buffer_inv sc0 sc1
	s_waitcnt vmcnt(0)
